# grid barrier: non-leader workgroups poll the cross-XCD release generation directly (no relay through the per-XCD word)
# speedup vs baseline: 1.0019x; 1.0011x over previous
.LBB0_54:
	s_or_b64 exec, exec, s[8:9]
	v_cvt_f32_u32_e32 v4, v2
	s_waitcnt vmcnt(0)
	v_readfirstlane_b32 s0, v3
	v_sub_u32_e32 v3, 0, v2
	v_rcp_iflag_f32_e32 v4, v4
	v_add_u32_e32 v5, s0, v1
	v_mul_f32_e32 v4, 0x4f7ffffe, v4
	v_cvt_u32_f32_e32 v4, v4
	v_mul_lo_u32 v1, v3, v4
	v_mul_hi_u32 v1, v4, v1
	v_add_u32_e32 v1, v4, v1
	v_mul_hi_u32 v1, v5, v1
	v_mul_lo_u32 v3, v1, v2
	v_sub_u32_e32 v3, v5, v3
	v_add_u32_e32 v4, 1, v1
	v_cmp_ge_u32_e32 vcc, v3, v2
	s_nop 1
	v_cndmask_b32_e32 v1, v1, v4, vcc
	v_sub_u32_e32 v4, v3, v2
	v_cndmask_b32_e32 v3, v3, v4, vcc
	v_add_u32_e32 v4, 1, v1
	v_cmp_ge_u32_e32 vcc, v3, v2
	v_add_u32_e32 v3, 1, v5
	s_nop 0
	v_cndmask_b32_e32 v1, v1, v4, vcc
	v_mul_lo_u32 v4, v2, v1
	v_add_u32_e32 v2, v4, v2
	v_cmp_ne_u32_e32 vcc, v3, v2
	s_and_saveexec_b64 s[0:1], vcc
	s_xor_b64 s[8:9], exec, s[0:1]
	s_cbranch_execz .LBB0_68
	v_readlane_b32 s0, v255, 20
	v_readlane_b32 s1, v255, 21
	s_waitcnt lgkmcnt(0)
	s_nop 3
	buffer_inv sc1
	global_load_dword v0, v197, s[0:1] sc1
	s_waitcnt vmcnt(0)
	v_cmp_eq_u32_e32 vcc, v0, v1
	s_and_saveexec_b64 s[12:13], vcc
	s_cbranch_execz .LBB0_67
	s_mov_b32 s0, 1
	s_mov_b64 s[14:15], 0
	s_branch .LBB0_58

.LBB0_62:
	v_readlane_b32 s2, v255, 20
	v_readlane_b32 s3, v255, 21
	s_add_i32 s0, s0, 1
	s_mov_b64 s[38:39], -1
	s_nop 2
	global_load_dword v0, v197, s[2:3] sc1
	s_waitcnt vmcnt(0)
	v_cmp_ne_u32_e32 vcc, v0, v1
	s_orn2_b64 s[18:19], vcc, exec
	s_branch .LBB0_57
